# P6 halo-row fix-up rewritten: 8 channels per thread, 16-byte loads issued together, one 16-byte store
# speedup vs baseline: 1.0457x; 1.0190x over previous
.LBB0_68:
	s_and_saveexec_b64 s[16:17], s[36:37]
	s_cbranch_execz .LBB0_67
	s_and_b32 s33, s2, 63
	s_and_b32 s0, s33, 7
	s_cmp_eq_u32 s0, 0
	s_cselect_b64 s[40:41], -1, 0
	s_lshl_b32 s42, s33, 2
	s_add_i32 s42, s42, -2
	s_mul_i32 s43, s33, 0x160000
	v_mov_b32_e32 v14, v12
	v_cmp_le_u32_e32 vcc, 0x160, v14
	s_mov_b64 s[68:69], vcc
	s_andn2_b64 s[44:45], s[40:41], s[68:69]
	v_cndmask_b32_e64 v15, 0, 1, s[68:69]
	v_mul_u32_u24_e32 v16, 0x160, v15
	v_sub_u32_e32 v16, v14, v16
	v_and_b32_e32 v17, 0xfffffff0, v16
	v_and_b32_e32 v30, 15, v16
	v_lshlrev_b32_e32 v17, 5, v17
	v_lshl_add_u32 v17, v30, 4, v17
	v_lshlrev_b32_e32 v18, 5, v16
	v_add_u32_e32 v19, s42, v15
	s_movk_i32 s0, 0x2c00
	v_max_i32_e32 v30, 0, v19
	v_mad_u32_u24 v20, v30, s0, v17
	v_add_u32_e32 v30, 1, v19
	v_max_i32_e32 v30, 0, v30
	v_mad_u32_u24 v21, v30, s0, v17
	v_add_u32_e32 v30, 2, v19
	v_mad_u32_u24 v22, v30, s0, v17
	v_add_u32_e32 v24, 0x2c00, v18
	v_add_u32_e32 v25, 0x5800, v18
	v_add_u32_e32 v26, 0x8400, v18
	v_add_u32_e32 v27, 0xb000, v18
	v_add_u32_e32 v28, 0xdc00, v18
	v_mov_b32_e32 v23, v18
	v_mul_u32_u24_e32 v29, 0x1600, v15
	v_lshl_add_u32 v29, v16, 4, v29
	v_add_u32_e32 v29, s43, v29
	global_load_dwordx4 v[32:35], v20, s[58:59]
	global_load_dwordx4 v[36:39], v20, s[58:59] offset:256
	global_load_dwordx4 v[40:43], v21, s[58:59]
	global_load_dwordx4 v[44:47], v21, s[58:59] offset:256
	global_load_dwordx4 v[48:51], v22, s[58:59]
	global_load_dwordx4 v[52:55], v22, s[58:59] offset:256
	global_load_dwordx4 v[56:59], v23, s[86:87]
	global_load_dwordx4 v[60:63], v23, s[86:87] offset:16
	global_load_dwordx4 v[64:67], v24, s[86:87]
	global_load_dwordx4 v[68:71], v24, s[86:87] offset:16
	global_load_dwordx4 v[72:75], v25, s[86:87]
	global_load_dwordx4 v[76:79], v25, s[86:87] offset:16
	global_load_dwordx4 v[80:83], v26, s[86:87]
	global_load_dwordx4 v[84:87], v26, s[86:87] offset:16
	global_load_dwordx4 v[88:91], v27, s[86:87]
	global_load_dwordx4 v[92:95], v27, s[86:87] offset:16
	global_load_dwordx4 v[96:99], v28, s[86:87]
	global_load_dwordx4 v[100:103], v28, s[86:87] offset:16
	global_load_dwordx4 v[104:107], v23, s[88:89]
	global_load_dwordx4 v[108:111], v23, s[88:89] offset:16
	global_load_dwordx4 v[112:115], v24, s[88:89]
	global_load_dwordx4 v[116:119], v24, s[88:89] offset:16
	s_waitcnt vmcnt(16)
	v_cndmask_b32_e64 v32, v32, 0, s[40:41]
	v_cndmask_b32_e64 v36, v36, 0, s[40:41]
	v_cndmask_b32_e64 v40, v40, 0, s[44:45]
	v_cndmask_b32_e64 v44, v44, 0, s[44:45]
	v_cndmask_b32_e64 v33, v33, 0, s[40:41]
	v_cndmask_b32_e64 v37, v37, 0, s[40:41]
	v_cndmask_b32_e64 v41, v41, 0, s[44:45]
	v_cndmask_b32_e64 v45, v45, 0, s[44:45]
	v_cndmask_b32_e64 v34, v34, 0, s[40:41]
	v_cndmask_b32_e64 v38, v38, 0, s[40:41]
	v_cndmask_b32_e64 v42, v42, 0, s[44:45]
	v_cndmask_b32_e64 v46, v46, 0, s[44:45]
	v_cndmask_b32_e64 v35, v35, 0, s[40:41]
	v_cndmask_b32_e64 v39, v39, 0, s[40:41]
	v_cndmask_b32_e64 v43, v43, 0, s[44:45]
	v_cndmask_b32_e64 v47, v47, 0, s[44:45]
	s_waitcnt vmcnt(0)
	v_lshlrev_b32_e32 v120, 16, v32
	v_lshlrev_b32_e32 v123, 16, v36
	v_lshlrev_b32_e32 v121, 16, v40
	v_lshlrev_b32_e32 v124, 16, v44
	v_lshlrev_b32_e32 v122, 16, v48
	v_lshlrev_b32_e32 v125, 16, v52
	v_mul_f32_e32 v126, v56, v120
	v_mul_f32_e32 v127, v64, v123
	v_fmac_f32_e32 v126, v72, v121
	v_fmac_f32_e32 v127, v80, v124
	v_fmac_f32_e32 v126, v88, v122
	v_fmac_f32_e32 v127, v96, v125
	v_add_f32_e32 v126, v104, v126
	v_add_f32_e32 v127, v112, v127
	v_mul_f32_e32 v128, 0xbfb8aa3b, v126
	v_exp_f32_e32 v128, v128
	s_nop 0
	v_add_f32_e32 v128, 1.0, v128
	v_rcp_f32_e32 v128, v128
	s_nop 0
	v_mul_f32_e32 v126, v126, v128
	v_mul_f32_e32 v140, v127, v126
	v_and_b32_e32 v120, 0xffff0000, v32
	v_and_b32_e32 v123, 0xffff0000, v36
	v_and_b32_e32 v121, 0xffff0000, v40
	v_and_b32_e32 v124, 0xffff0000, v44
	v_and_b32_e32 v122, 0xffff0000, v48
	v_and_b32_e32 v125, 0xffff0000, v52
	v_mul_f32_e32 v126, v57, v120
	v_mul_f32_e32 v127, v65, v123
	v_fmac_f32_e32 v126, v73, v121
	v_fmac_f32_e32 v127, v81, v124
	v_fmac_f32_e32 v126, v89, v122
	v_fmac_f32_e32 v127, v97, v125
	v_add_f32_e32 v126, v105, v126
	v_add_f32_e32 v127, v113, v127
	v_mul_f32_e32 v128, 0xbfb8aa3b, v126
	v_exp_f32_e32 v128, v128
	s_nop 0
	v_add_f32_e32 v128, 1.0, v128
	v_rcp_f32_e32 v128, v128
	s_nop 0
	v_mul_f32_e32 v126, v126, v128
	v_mul_f32_e32 v141, v127, v126
	v_lshlrev_b32_e32 v120, 16, v33
	v_lshlrev_b32_e32 v123, 16, v37
	v_lshlrev_b32_e32 v121, 16, v41
	v_lshlrev_b32_e32 v124, 16, v45
	v_lshlrev_b32_e32 v122, 16, v49
	v_lshlrev_b32_e32 v125, 16, v53
	v_mul_f32_e32 v126, v58, v120
	v_mul_f32_e32 v127, v66, v123
	v_fmac_f32_e32 v126, v74, v121
	v_fmac_f32_e32 v127, v82, v124
	v_fmac_f32_e32 v126, v90, v122
	v_fmac_f32_e32 v127, v98, v125
	v_add_f32_e32 v126, v106, v126
	v_add_f32_e32 v127, v114, v127
	v_mul_f32_e32 v128, 0xbfb8aa3b, v126
	v_exp_f32_e32 v128, v128
	s_nop 0
	v_add_f32_e32 v128, 1.0, v128
	v_rcp_f32_e32 v128, v128
	s_nop 0
	v_mul_f32_e32 v126, v126, v128
	v_mul_f32_e32 v142, v127, v126
	v_and_b32_e32 v120, 0xffff0000, v33
	v_and_b32_e32 v123, 0xffff0000, v37
	v_and_b32_e32 v121, 0xffff0000, v41
	v_and_b32_e32 v124, 0xffff0000, v45
	v_and_b32_e32 v122, 0xffff0000, v49
	v_and_b32_e32 v125, 0xffff0000, v53
	v_mul_f32_e32 v126, v59, v120
	v_mul_f32_e32 v127, v67, v123
	v_fmac_f32_e32 v126, v75, v121
	v_fmac_f32_e32 v127, v83, v124
	v_fmac_f32_e32 v126, v91, v122
	v_fmac_f32_e32 v127, v99, v125
	v_add_f32_e32 v126, v107, v126
	v_add_f32_e32 v127, v115, v127
	v_mul_f32_e32 v128, 0xbfb8aa3b, v126
	v_exp_f32_e32 v128, v128
	s_nop 0
	v_add_f32_e32 v128, 1.0, v128
	v_rcp_f32_e32 v128, v128
	s_nop 0
	v_mul_f32_e32 v126, v126, v128
	v_mul_f32_e32 v143, v127, v126
	v_lshlrev_b32_e32 v120, 16, v34
	v_lshlrev_b32_e32 v123, 16, v38
	v_lshlrev_b32_e32 v121, 16, v42
	v_lshlrev_b32_e32 v124, 16, v46
	v_lshlrev_b32_e32 v122, 16, v50
	v_lshlrev_b32_e32 v125, 16, v54
	v_mul_f32_e32 v126, v60, v120
	v_mul_f32_e32 v127, v68, v123
	v_fmac_f32_e32 v126, v76, v121
	v_fmac_f32_e32 v127, v84, v124
	v_fmac_f32_e32 v126, v92, v122
	v_fmac_f32_e32 v127, v100, v125
	v_add_f32_e32 v126, v108, v126
	v_add_f32_e32 v127, v116, v127
	v_mul_f32_e32 v128, 0xbfb8aa3b, v126
	v_exp_f32_e32 v128, v128
	s_nop 0
	v_add_f32_e32 v128, 1.0, v128
	v_rcp_f32_e32 v128, v128
	s_nop 0
	v_mul_f32_e32 v126, v126, v128
	v_mul_f32_e32 v144, v127, v126
	v_and_b32_e32 v120, 0xffff0000, v34
	v_and_b32_e32 v123, 0xffff0000, v38
	v_and_b32_e32 v121, 0xffff0000, v42
	v_and_b32_e32 v124, 0xffff0000, v46
	v_and_b32_e32 v122, 0xffff0000, v50
	v_and_b32_e32 v125, 0xffff0000, v54
	v_mul_f32_e32 v126, v61, v120
	v_mul_f32_e32 v127, v69, v123
	v_fmac_f32_e32 v126, v77, v121
	v_fmac_f32_e32 v127, v85, v124
	v_fmac_f32_e32 v126, v93, v122
	v_fmac_f32_e32 v127, v101, v125
	v_add_f32_e32 v126, v109, v126
	v_add_f32_e32 v127, v117, v127
	v_mul_f32_e32 v128, 0xbfb8aa3b, v126
	v_exp_f32_e32 v128, v128
	s_nop 0
	v_add_f32_e32 v128, 1.0, v128
	v_rcp_f32_e32 v128, v128
	s_nop 0
	v_mul_f32_e32 v126, v126, v128
	v_mul_f32_e32 v145, v127, v126
	v_lshlrev_b32_e32 v120, 16, v35
	v_lshlrev_b32_e32 v123, 16, v39
	v_lshlrev_b32_e32 v121, 16, v43
	v_lshlrev_b32_e32 v124, 16, v47
	v_lshlrev_b32_e32 v122, 16, v51
	v_lshlrev_b32_e32 v125, 16, v55
	v_mul_f32_e32 v126, v62, v120
	v_mul_f32_e32 v127, v70, v123
	v_fmac_f32_e32 v126, v78, v121
	v_fmac_f32_e32 v127, v86, v124
	v_fmac_f32_e32 v126, v94, v122
	v_fmac_f32_e32 v127, v102, v125
	v_add_f32_e32 v126, v110, v126
	v_add_f32_e32 v127, v118, v127
	v_mul_f32_e32 v128, 0xbfb8aa3b, v126
	v_exp_f32_e32 v128, v128
	s_nop 0
	v_add_f32_e32 v128, 1.0, v128
	v_rcp_f32_e32 v128, v128
	s_nop 0
	v_mul_f32_e32 v126, v126, v128
	v_mul_f32_e32 v146, v127, v126
	v_and_b32_e32 v120, 0xffff0000, v35
	v_and_b32_e32 v123, 0xffff0000, v39
	v_and_b32_e32 v121, 0xffff0000, v43
	v_and_b32_e32 v124, 0xffff0000, v47
	v_and_b32_e32 v122, 0xffff0000, v51
	v_and_b32_e32 v125, 0xffff0000, v55
	v_mul_f32_e32 v126, v63, v120
	v_mul_f32_e32 v127, v71, v123
	v_fmac_f32_e32 v126, v79, v121
	v_fmac_f32_e32 v127, v87, v124
	v_fmac_f32_e32 v126, v95, v122
	v_fmac_f32_e32 v127, v103, v125
	v_add_f32_e32 v126, v111, v126
	v_add_f32_e32 v127, v119, v127
	v_mul_f32_e32 v128, 0xbfb8aa3b, v126
	v_exp_f32_e32 v128, v128
	s_nop 0
	v_add_f32_e32 v128, 1.0, v128
	v_rcp_f32_e32 v128, v128
	s_nop 0
	v_mul_f32_e32 v126, v126, v128
	v_mul_f32_e32 v147, v127, v126
	v_cvt_pk_bf16_f32 v136, v140, v141
	v_cvt_pk_bf16_f32 v137, v142, v143
	v_cvt_pk_bf16_f32 v138, v144, v145
	v_cvt_pk_bf16_f32 v139, v146, v147
	global_store_dwordx4 v29, v[136:139], s[60:61]
	v_cmp_gt_u32_e32 vcc, 0xc0, v12
	s_and_saveexec_b64 s[70:71], vcc
	s_cbranch_execz .Lfix_done
	v_add_u32_e32 v14, 0x200, v12
	v_cmp_le_u32_e32 vcc, 0x160, v14
	s_mov_b64 s[68:69], vcc
	s_andn2_b64 s[44:45], s[40:41], s[68:69]
	v_cndmask_b32_e64 v15, 0, 1, s[68:69]
	v_mul_u32_u24_e32 v16, 0x160, v15
	v_sub_u32_e32 v16, v14, v16
	v_and_b32_e32 v17, 0xfffffff0, v16
	v_and_b32_e32 v30, 15, v16
	v_lshlrev_b32_e32 v17, 5, v17
	v_lshl_add_u32 v17, v30, 4, v17
	v_lshlrev_b32_e32 v18, 5, v16
	v_add_u32_e32 v19, s42, v15
	s_movk_i32 s0, 0x2c00
	v_max_i32_e32 v30, 0, v19
	v_mad_u32_u24 v20, v30, s0, v17
	v_add_u32_e32 v30, 1, v19
	v_max_i32_e32 v30, 0, v30
	v_mad_u32_u24 v21, v30, s0, v17
	v_add_u32_e32 v30, 2, v19
	v_mad_u32_u24 v22, v30, s0, v17
	v_add_u32_e32 v24, 0x2c00, v18
	v_add_u32_e32 v25, 0x5800, v18
	v_add_u32_e32 v26, 0x8400, v18
	v_add_u32_e32 v27, 0xb000, v18
	v_add_u32_e32 v28, 0xdc00, v18
	v_mov_b32_e32 v23, v18
	v_mul_u32_u24_e32 v29, 0x1600, v15
	v_lshl_add_u32 v29, v16, 4, v29
	v_add_u32_e32 v29, s43, v29
	global_load_dwordx4 v[32:35], v20, s[58:59]
	global_load_dwordx4 v[36:39], v20, s[58:59] offset:256
	global_load_dwordx4 v[40:43], v21, s[58:59]
	global_load_dwordx4 v[44:47], v21, s[58:59] offset:256
	global_load_dwordx4 v[48:51], v22, s[58:59]
	global_load_dwordx4 v[52:55], v22, s[58:59] offset:256
	global_load_dwordx4 v[56:59], v23, s[86:87]
	global_load_dwordx4 v[60:63], v23, s[86:87] offset:16
	global_load_dwordx4 v[64:67], v24, s[86:87]
	global_load_dwordx4 v[68:71], v24, s[86:87] offset:16
	global_load_dwordx4 v[72:75], v25, s[86:87]
	global_load_dwordx4 v[76:79], v25, s[86:87] offset:16
	global_load_dwordx4 v[80:83], v26, s[86:87]
	global_load_dwordx4 v[84:87], v26, s[86:87] offset:16
	global_load_dwordx4 v[88:91], v27, s[86:87]
	global_load_dwordx4 v[92:95], v27, s[86:87] offset:16
	global_load_dwordx4 v[96:99], v28, s[86:87]
	global_load_dwordx4 v[100:103], v28, s[86:87] offset:16
	global_load_dwordx4 v[104:107], v23, s[88:89]
	global_load_dwordx4 v[108:111], v23, s[88:89] offset:16
	global_load_dwordx4 v[112:115], v24, s[88:89]
	global_load_dwordx4 v[116:119], v24, s[88:89] offset:16
	s_waitcnt vmcnt(16)
	v_cndmask_b32_e64 v32, v32, 0, s[40:41]
	v_cndmask_b32_e64 v36, v36, 0, s[40:41]
	v_cndmask_b32_e64 v40, v40, 0, s[44:45]
	v_cndmask_b32_e64 v44, v44, 0, s[44:45]
	v_cndmask_b32_e64 v33, v33, 0, s[40:41]
	v_cndmask_b32_e64 v37, v37, 0, s[40:41]
	v_cndmask_b32_e64 v41, v41, 0, s[44:45]
	v_cndmask_b32_e64 v45, v45, 0, s[44:45]
	v_cndmask_b32_e64 v34, v34, 0, s[40:41]
	v_cndmask_b32_e64 v38, v38, 0, s[40:41]
	v_cndmask_b32_e64 v42, v42, 0, s[44:45]
	v_cndmask_b32_e64 v46, v46, 0, s[44:45]
	v_cndmask_b32_e64 v35, v35, 0, s[40:41]
	v_cndmask_b32_e64 v39, v39, 0, s[40:41]
	v_cndmask_b32_e64 v43, v43, 0, s[44:45]
	v_cndmask_b32_e64 v47, v47, 0, s[44:45]
	s_waitcnt vmcnt(0)
	v_lshlrev_b32_e32 v120, 16, v32
	v_lshlrev_b32_e32 v123, 16, v36
	v_lshlrev_b32_e32 v121, 16, v40
	v_lshlrev_b32_e32 v124, 16, v44
	v_lshlrev_b32_e32 v122, 16, v48
	v_lshlrev_b32_e32 v125, 16, v52
	v_mul_f32_e32 v126, v56, v120
	v_mul_f32_e32 v127, v64, v123
	v_fmac_f32_e32 v126, v72, v121
	v_fmac_f32_e32 v127, v80, v124
	v_fmac_f32_e32 v126, v88, v122
	v_fmac_f32_e32 v127, v96, v125
	v_add_f32_e32 v126, v104, v126
	v_add_f32_e32 v127, v112, v127
	v_mul_f32_e32 v128, 0xbfb8aa3b, v126
	v_exp_f32_e32 v128, v128
	s_nop 0
	v_add_f32_e32 v128, 1.0, v128
	v_rcp_f32_e32 v128, v128
	s_nop 0
	v_mul_f32_e32 v126, v126, v128
	v_mul_f32_e32 v140, v127, v126
	v_and_b32_e32 v120, 0xffff0000, v32
	v_and_b32_e32 v123, 0xffff0000, v36
	v_and_b32_e32 v121, 0xffff0000, v40
	v_and_b32_e32 v124, 0xffff0000, v44
	v_and_b32_e32 v122, 0xffff0000, v48
	v_and_b32_e32 v125, 0xffff0000, v52
	v_mul_f32_e32 v126, v57, v120
	v_mul_f32_e32 v127, v65, v123
	v_fmac_f32_e32 v126, v73, v121
	v_fmac_f32_e32 v127, v81, v124
	v_fmac_f32_e32 v126, v89, v122
	v_fmac_f32_e32 v127, v97, v125
	v_add_f32_e32 v126, v105, v126
	v_add_f32_e32 v127, v113, v127
	v_mul_f32_e32 v128, 0xbfb8aa3b, v126
	v_exp_f32_e32 v128, v128
	s_nop 0
	v_add_f32_e32 v128, 1.0, v128
	v_rcp_f32_e32 v128, v128
	s_nop 0
	v_mul_f32_e32 v126, v126, v128
	v_mul_f32_e32 v141, v127, v126
	v_lshlrev_b32_e32 v120, 16, v33
	v_lshlrev_b32_e32 v123, 16, v37
	v_lshlrev_b32_e32 v121, 16, v41
	v_lshlrev_b32_e32 v124, 16, v45
	v_lshlrev_b32_e32 v122, 16, v49
	v_lshlrev_b32_e32 v125, 16, v53
	v_mul_f32_e32 v126, v58, v120
	v_mul_f32_e32 v127, v66, v123
	v_fmac_f32_e32 v126, v74, v121
	v_fmac_f32_e32 v127, v82, v124
	v_fmac_f32_e32 v126, v90, v122
	v_fmac_f32_e32 v127, v98, v125
	v_add_f32_e32 v126, v106, v126
	v_add_f32_e32 v127, v114, v127
	v_mul_f32_e32 v128, 0xbfb8aa3b, v126
	v_exp_f32_e32 v128, v128
	s_nop 0
	v_add_f32_e32 v128, 1.0, v128
	v_rcp_f32_e32 v128, v128
	s_nop 0
	v_mul_f32_e32 v126, v126, v128
	v_mul_f32_e32 v142, v127, v126
	v_and_b32_e32 v120, 0xffff0000, v33
	v_and_b32_e32 v123, 0xffff0000, v37
	v_and_b32_e32 v121, 0xffff0000, v41
	v_and_b32_e32 v124, 0xffff0000, v45
	v_and_b32_e32 v122, 0xffff0000, v49
	v_and_b32_e32 v125, 0xffff0000, v53
	v_mul_f32_e32 v126, v59, v120
	v_mul_f32_e32 v127, v67, v123
	v_fmac_f32_e32 v126, v75, v121
	v_fmac_f32_e32 v127, v83, v124
	v_fmac_f32_e32 v126, v91, v122
	v_fmac_f32_e32 v127, v99, v125
	v_add_f32_e32 v126, v107, v126
	v_add_f32_e32 v127, v115, v127
	v_mul_f32_e32 v128, 0xbfb8aa3b, v126
	v_exp_f32_e32 v128, v128
	s_nop 0
	v_add_f32_e32 v128, 1.0, v128
	v_rcp_f32_e32 v128, v128
	s_nop 0
	v_mul_f32_e32 v126, v126, v128
	v_mul_f32_e32 v143, v127, v126
	v_lshlrev_b32_e32 v120, 16, v34
	v_lshlrev_b32_e32 v123, 16, v38
	v_lshlrev_b32_e32 v121, 16, v42
	v_lshlrev_b32_e32 v124, 16, v46
	v_lshlrev_b32_e32 v122, 16, v50
	v_lshlrev_b32_e32 v125, 16, v54
	v_mul_f32_e32 v126, v60, v120
	v_mul_f32_e32 v127, v68, v123
	v_fmac_f32_e32 v126, v76, v121
	v_fmac_f32_e32 v127, v84, v124
	v_fmac_f32_e32 v126, v92, v122
	v_fmac_f32_e32 v127, v100, v125
	v_add_f32_e32 v126, v108, v126
	v_add_f32_e32 v127, v116, v127
	v_mul_f32_e32 v128, 0xbfb8aa3b, v126
	v_exp_f32_e32 v128, v128
	s_nop 0
	v_add_f32_e32 v128, 1.0, v128
	v_rcp_f32_e32 v128, v128
	s_nop 0
	v_mul_f32_e32 v126, v126, v128
	v_mul_f32_e32 v144, v127, v126
	v_and_b32_e32 v120, 0xffff0000, v34
	v_and_b32_e32 v123, 0xffff0000, v38
	v_and_b32_e32 v121, 0xffff0000, v42
	v_and_b32_e32 v124, 0xffff0000, v46
	v_and_b32_e32 v122, 0xffff0000, v50
	v_and_b32_e32 v125, 0xffff0000, v54
	v_mul_f32_e32 v126, v61, v120
	v_mul_f32_e32 v127, v69, v123
	v_fmac_f32_e32 v126, v77, v121
	v_fmac_f32_e32 v127, v85, v124
	v_fmac_f32_e32 v126, v93, v122
	v_fmac_f32_e32 v127, v101, v125
	v_add_f32_e32 v126, v109, v126
	v_add_f32_e32 v127, v117, v127
	v_mul_f32_e32 v128, 0xbfb8aa3b, v126
	v_exp_f32_e32 v128, v128
	s_nop 0
	v_add_f32_e32 v128, 1.0, v128
	v_rcp_f32_e32 v128, v128
	s_nop 0
	v_mul_f32_e32 v126, v126, v128
	v_mul_f32_e32 v145, v127, v126
	v_lshlrev_b32_e32 v120, 16, v35
	v_lshlrev_b32_e32 v123, 16, v39
	v_lshlrev_b32_e32 v121, 16, v43
	v_lshlrev_b32_e32 v124, 16, v47
	v_lshlrev_b32_e32 v122, 16, v51
	v_lshlrev_b32_e32 v125, 16, v55
	v_mul_f32_e32 v126, v62, v120
	v_mul_f32_e32 v127, v70, v123
	v_fmac_f32_e32 v126, v78, v121
	v_fmac_f32_e32 v127, v86, v124
	v_fmac_f32_e32 v126, v94, v122
	v_fmac_f32_e32 v127, v102, v125
	v_add_f32_e32 v126, v110, v126
	v_add_f32_e32 v127, v118, v127
	v_mul_f32_e32 v128, 0xbfb8aa3b, v126
	v_exp_f32_e32 v128, v128
	s_nop 0
	v_add_f32_e32 v128, 1.0, v128
	v_rcp_f32_e32 v128, v128
	s_nop 0
	v_mul_f32_e32 v126, v126, v128
	v_mul_f32_e32 v146, v127, v126
	v_and_b32_e32 v120, 0xffff0000, v35
	v_and_b32_e32 v123, 0xffff0000, v39
	v_and_b32_e32 v121, 0xffff0000, v43
	v_and_b32_e32 v124, 0xffff0000, v47
	v_and_b32_e32 v122, 0xffff0000, v51
	v_and_b32_e32 v125, 0xffff0000, v55
	v_mul_f32_e32 v126, v63, v120
	v_mul_f32_e32 v127, v71, v123
	v_fmac_f32_e32 v126, v79, v121
	v_fmac_f32_e32 v127, v87, v124
	v_fmac_f32_e32 v126, v95, v122
	v_fmac_f32_e32 v127, v103, v125
	v_add_f32_e32 v126, v111, v126
	v_add_f32_e32 v127, v119, v127
	v_mul_f32_e32 v128, 0xbfb8aa3b, v126
	v_exp_f32_e32 v128, v128
	s_nop 0
	v_add_f32_e32 v128, 1.0, v128
	v_rcp_f32_e32 v128, v128
	s_nop 0
	v_mul_f32_e32 v126, v126, v128
	v_mul_f32_e32 v147, v127, v126
	v_cvt_pk_bf16_f32 v136, v140, v141
	v_cvt_pk_bf16_f32 v137, v142, v143
	v_cvt_pk_bf16_f32 v138, v144, v145
	v_cvt_pk_bf16_f32 v139, v146, v147
	global_store_dwordx4 v29, v[136:139], s[60:61]
.Lfix_done:
	s_or_b64 exec, exec, s[70:71]
	s_branch .LBB0_67
